# tail share: GEMM half converts 192 (was 256) of HG_IN's 512 row blocks after its units, the converting half the rest
# speedup vs baseline: 1.0082x; 1.0049x over previous
; __device__ __forceinline__ void p0_split_tail(Frame& F, int my, int nconv) {
;     const int gw0 = F.gw, ngw0 = F.ngw; F.gw = my * NWAVES + F.wave; F.ngw = nconv * NWAVES;
;     int it0 = 0;
;     p0_transpose_matrix2(F, FIN(F, 15), DM, HG_NP, (bf16*)FW(F, WS_W_HG_IN), HG_NP / 32 - P_HG_SPLIT, [](int nb) { return (P_HG_SPLIT + nb) * 32; }, [](int nb) { return (P_HG_SPLIT + nb) * 32; }, it0, FIN(F, 1) + 2 * DM);
;     F.gw = gw0; F.ngw = ngw0;
; }
.LBB0_260:
	v_readlane_b32 s4, v254, 7
	v_readlane_b32 s5, v254, 8
	s_waitcnt vmcnt(0)
	s_barrier
	s_barrier
	v_readlane_b32 s62, v254, 7
	v_readlane_b32 s63, v254, 8
	s_nop 3
	s_load_dwordx2 s[44:45], s[62:63], 0x78
	s_load_dwordx2 s[52:53], s[62:63], 0x8
	s_waitcnt lgkmcnt(0)
	s_add_u32 s52, s52, 0x8000
	s_addc_u32 s53, s53, 0
	s_mov_b32 s46, 0x10000
	s_mov_b32 s47, 0
	s_add_u32 s48, s70, 0x15600000
	s_addc_u32 s49, s71, 0
	s_mov_b32 s50, 48
	s_mov_b32 s51, 0x100015
	s_mov_b32 s54, 320
	s_mov_b32 s55, 0
	s_lshl_b32 s56, s33, 3
	s_add_i32 s56, s56, s90
	s_mov_b32 s32, 0
	s_branch .Lcva_run

; __device__ __forceinline__ void p0_split_convert(Frame& F, int my, int nconv, unsigned* flag) {
;     ...
;     p0_transpose_matrix(F, FIN(F, 15), DM, HG_NP, (bf16*)FW(F, WS_W_HG_IN), P_HG_SPLIT, [](int nb) { return nb * 32; }, it0, FIN(F, 1) + 2 * DM);
.Lcv_ret3:
	v_readlane_b32 s62, v254, 7
	v_readlane_b32 s63, v254, 8
	s_nop 3
	s_load_dwordx2 s[44:45], s[62:63], 0x78
	s_load_dwordx2 s[52:53], s[62:63], 0x8
	s_waitcnt lgkmcnt(0)
	s_add_u32 s52, s52, 0x8000
	s_addc_u32 s53, s53, 0
	s_mov_b32 s46, 0x10000
	s_mov_b32 s47, 0
	s_add_u32 s48, s70, 0x15600000
	s_addc_u32 s49, s71, 0
	s_mov_b32 s50, 80
	s_mov_b32 s51, 0x40000c
	s_mov_b32 s54, 0
	s_mov_b32 s55, 640
	s_mov_b32 s56, s19
	s_mov_b32 s32, 4
	s_branch .Lcva_run
